# attnA softmax: lazy running max (threshold 8 in log2 domain, as attnC) and rescale skipped when alpha is 1
# speedup vs baseline: 1.1308x; 1.0018x over previous
; __device__ __forceinline__ float fexp2(float x) { return __builtin_amdgcn_exp2f(x); }
; template <bool KLDS>
; __device__ __forceinline__ void attn_step(const bf16x8 (&kf)[4], LAS const unsigned char* kb, const bf16x8 (&vf)[2][2], const bf16x8 (&qf)[4], f32x16& o0, f32x16& o1, float& m, float& l, int lane, int maskmode) {
;     ...
;     float tm = S[0];
; #pragma unroll
;     for (int i = 1; i < 16; ++i) tm = fmaxf(tm, S[i]);
;     tm = fmaxf(tm, __shfl_xor(tm, 32));
;     const float mn = fmaxf(m, tm), al = fexp2(m - mn); m = mn;
;     float ps = 0.f;
; #pragma unroll
;     for (int i = 0; i < 16; ++i) { S[i] = fexp2(S[i] - mn); ps += S[i]; }
;     l = l * al + ps;
; #pragma unroll
;     for (int i = 0; i < 16; ++i) { o0[i] *= al; o1[i] *= al; }
.LaT_ndb:
	s_add_i32 s80, s80, 32
	s_mov_b32 s32, 0x41000000
	v_max3_f32 v138, v32, v33, v34
	v_max3_f32 v148, v96, v97, v98
	v_max3_f32 v138, v138, v35, v36
	v_max3_f32 v148, v148, v99, v100
	v_max3_f32 v138, v138, v37, v38
	v_max3_f32 v148, v148, v101, v102
	v_max3_f32 v138, v138, v39, v40
	v_max3_f32 v148, v148, v103, v104
	v_max3_f32 v138, v138, v41, v42
	v_max3_f32 v148, v148, v105, v106
	v_max3_f32 v138, v138, v43, v44
	v_max3_f32 v148, v148, v107, v108
	v_max3_f32 v138, v138, v45, v46
	v_max3_f32 v148, v148, v109, v110
	v_max_f32_e32 v138, v138, v47
	v_max_f32_e32 v148, v148, v111
	v_mov_b32_e32 v139, v138
	v_mov_b32_e32 v149, v148
	s_nop 1
	s_nop 1
	v_permlane32_swap_b32_e32 v139, v138
	v_permlane32_swap_b32_e32 v149, v148
	v_max_f32_e32 v138, v138, v139
	v_max_f32_e32 v148, v148, v149
	v_sub_f32_e32 v139, v138, v137
	v_sub_f32_e32 v149, v148, v212
	v_cmp_lt_f32_e64 s[0:1], s32, v139
	v_cmp_lt_f32_e64 s[98:99], s32, v149
	s_nop 1
	s_nop 1
	v_cndmask_b32_e64 v220, v137, v138, s[0:1]
	v_cndmask_b32_e64 v222, v212, v148, s[98:99]
	v_sub_f32_e32 v140, v137, v220
	v_sub_f32_e32 v150, v212, v222
	v_exp_f32_e32 v140, v140
	v_exp_f32_e32 v150, v150
	v_mov_b32_e32 v137, v220
	v_mov_b32_e32 v212, v222
	v_cmp_neq_f32_e32 vcc, 1.0, v140
	s_cbranch_vccz .LaP_nrza
	s_nop 15
	s_nop 15
	s_nop 15
	v_pk_mul_f32 v[16:17], v[16:17], v[140:141] op_sel_hi:[1,0]
	v_pk_mul_f32 v[18:19], v[18:19], v[140:141] op_sel_hi:[1,0]
	v_pk_mul_f32 v[20:21], v[20:21], v[140:141] op_sel_hi:[1,0]
	v_pk_mul_f32 v[22:23], v[22:23], v[140:141] op_sel_hi:[1,0]
	v_pk_mul_f32 v[24:25], v[24:25], v[140:141] op_sel_hi:[1,0]
	v_pk_mul_f32 v[26:27], v[26:27], v[140:141] op_sel_hi:[1,0]
	v_pk_mul_f32 v[28:29], v[28:29], v[140:141] op_sel_hi:[1,0]
	v_pk_mul_f32 v[30:31], v[30:31], v[140:141] op_sel_hi:[1,0]
	v_pk_mul_f32 v[0:1], v[0:1], v[140:141] op_sel_hi:[1,0]
	v_pk_mul_f32 v[2:3], v[2:3], v[140:141] op_sel_hi:[1,0]
	v_pk_mul_f32 v[4:5], v[4:5], v[140:141] op_sel_hi:[1,0]
	v_pk_mul_f32 v[6:7], v[6:7], v[140:141] op_sel_hi:[1,0]
	v_pk_mul_f32 v[8:9], v[8:9], v[140:141] op_sel_hi:[1,0]
	v_pk_mul_f32 v[10:11], v[10:11], v[140:141] op_sel_hi:[1,0]
	v_pk_mul_f32 v[12:13], v[12:13], v[140:141] op_sel_hi:[1,0]
	v_pk_mul_f32 v[14:15], v[14:15], v[140:141] op_sel_hi:[1,0]
.LaP_nrza:
	v_cmp_neq_f32_e32 vcc, 1.0, v150
	s_cbranch_vccz .LaP_nrzb
	s_nop 15
	s_nop 15
	s_nop 15
	v_pk_mul_f32 v[80:81], v[80:81], v[150:151] op_sel_hi:[1,0]
	v_pk_mul_f32 v[82:83], v[82:83], v[150:151] op_sel_hi:[1,0]
	v_pk_mul_f32 v[84:85], v[84:85], v[150:151] op_sel_hi:[1,0]
	v_pk_mul_f32 v[86:87], v[86:87], v[150:151] op_sel_hi:[1,0]
	v_pk_mul_f32 v[88:89], v[88:89], v[150:151] op_sel_hi:[1,0]
	v_pk_mul_f32 v[90:91], v[90:91], v[150:151] op_sel_hi:[1,0]
	v_pk_mul_f32 v[92:93], v[92:93], v[150:151] op_sel_hi:[1,0]
	v_pk_mul_f32 v[94:95], v[94:95], v[150:151] op_sel_hi:[1,0]
	v_pk_mul_f32 v[64:65], v[64:65], v[150:151] op_sel_hi:[1,0]
	v_pk_mul_f32 v[66:67], v[66:67], v[150:151] op_sel_hi:[1,0]
	v_pk_mul_f32 v[68:69], v[68:69], v[150:151] op_sel_hi:[1,0]
	v_pk_mul_f32 v[70:71], v[70:71], v[150:151] op_sel_hi:[1,0]
	v_pk_mul_f32 v[72:73], v[72:73], v[150:151] op_sel_hi:[1,0]
	v_pk_mul_f32 v[74:75], v[74:75], v[150:151] op_sel_hi:[1,0]
	v_pk_mul_f32 v[76:77], v[76:77], v[150:151] op_sel_hi:[1,0]
	v_pk_mul_f32 v[78:79], v[78:79], v[150:151] op_sel_hi:[1,0]
.LaP_nrzb:
	v_pk_add_f32 v[32:33], v[32:33], v[220:221] op_sel_hi:[1,0] neg_lo:[0,1] neg_hi:[0,1]
	v_pk_add_f32 v[96:97], v[96:97], v[222:223] op_sel_hi:[1,0] neg_lo:[0,1] neg_hi:[0,1]
	v_pk_add_f32 v[34:35], v[34:35], v[220:221] op_sel_hi:[1,0] neg_lo:[0,1] neg_hi:[0,1]
	v_pk_add_f32 v[98:99], v[98:99], v[222:223] op_sel_hi:[1,0] neg_lo:[0,1] neg_hi:[0,1]
	v_pk_add_f32 v[36:37], v[36:37], v[220:221] op_sel_hi:[1,0] neg_lo:[0,1] neg_hi:[0,1]
	v_pk_add_f32 v[100:101], v[100:101], v[222:223] op_sel_hi:[1,0] neg_lo:[0,1] neg_hi:[0,1]
	v_pk_add_f32 v[38:39], v[38:39], v[220:221] op_sel_hi:[1,0] neg_lo:[0,1] neg_hi:[0,1]
	v_pk_add_f32 v[102:103], v[102:103], v[222:223] op_sel_hi:[1,0] neg_lo:[0,1] neg_hi:[0,1]
	v_pk_add_f32 v[40:41], v[40:41], v[220:221] op_sel_hi:[1,0] neg_lo:[0,1] neg_hi:[0,1]
	v_pk_add_f32 v[104:105], v[104:105], v[222:223] op_sel_hi:[1,0] neg_lo:[0,1] neg_hi:[0,1]
	v_pk_add_f32 v[42:43], v[42:43], v[220:221] op_sel_hi:[1,0] neg_lo:[0,1] neg_hi:[0,1]
	v_pk_add_f32 v[106:107], v[106:107], v[222:223] op_sel_hi:[1,0] neg_lo:[0,1] neg_hi:[0,1]
	v_pk_add_f32 v[44:45], v[44:45], v[220:221] op_sel_hi:[1,0] neg_lo:[0,1] neg_hi:[0,1]
	v_pk_add_f32 v[108:109], v[108:109], v[222:223] op_sel_hi:[1,0] neg_lo:[0,1] neg_hi:[0,1]
	v_pk_add_f32 v[46:47], v[46:47], v[220:221] op_sel_hi:[1,0] neg_lo:[0,1] neg_hi:[0,1]
	v_pk_add_f32 v[110:111], v[110:111], v[222:223] op_sel_hi:[1,0] neg_lo:[0,1] neg_hi:[0,1]
	v_exp_f32_e32 v32, v32
	v_exp_f32_e32 v96, v96
	v_exp_f32_e32 v33, v33
	v_exp_f32_e32 v97, v97
	v_exp_f32_e32 v34, v34
	v_exp_f32_e32 v98, v98
	v_exp_f32_e32 v35, v35
	v_exp_f32_e32 v99, v99
	v_pk_add_f32 v[152:153], v[32:33], v[34:35]
	v_pk_add_f32 v[218:219], v[96:97], v[98:99]
	v_exp_f32_e32 v36, v36
	v_exp_f32_e32 v100, v100
	v_exp_f32_e32 v37, v37
	v_exp_f32_e32 v101, v101
	v_pk_add_f32 v[152:153], v[152:153], v[36:37]
	v_pk_add_f32 v[218:219], v[218:219], v[100:101]
	v_exp_f32_e32 v38, v38
	v_exp_f32_e32 v102, v102
	v_exp_f32_e32 v39, v39
	v_exp_f32_e32 v103, v103
	v_pk_add_f32 v[152:153], v[152:153], v[38:39]
	v_pk_add_f32 v[218:219], v[218:219], v[102:103]
	v_exp_f32_e32 v40, v40
	v_exp_f32_e32 v104, v104
	v_exp_f32_e32 v41, v41
	v_exp_f32_e32 v105, v105
	v_pk_add_f32 v[152:153], v[152:153], v[40:41]
	v_pk_add_f32 v[218:219], v[218:219], v[104:105]
; __device__ __forceinline__ unsigned pk2(float lo, float hi) { unsigned r; asm("v_cvt_pk_bf16_f32 %0, %1, %2" : "=v"(r) : "v"(lo), "v"(hi)); return r; }
; __device__ __forceinline__ unsigned pk2n(float lo, float hi) { const f32x2v v = {lo, hi}; const bf16v2 b = __builtin_convertvector(v, bf16v2); return __builtin_bit_cast(unsigned, b); }
; __device__ __forceinline__ float fexp2(float x) { return __builtin_amdgcn_exp2f(x); }
; template <bool KLDS>
; __device__ __forceinline__ void attn_step(const bf16x8 (&kf)[4], LAS const unsigned char* kb, const bf16x8 (&vf)[2][2], const bf16x8 (&qf)[4], f32x16& o0, f32x16& o1, float& m, float& l, int lane, int maskmode) {
;     ...
;     for (int i = 0; i < 16; ++i) { S[i] = fexp2(S[i] - mn); ps += S[i]; }
;     l = l * al + ps;
; #pragma unroll
;     for (int i = 0; i < 16; ++i) { o0[i] *= al; o1[i] *= al; }
;     bf16x8 pf[2];
; #pragma unroll
;     for (int s2 = 0; s2 < 2; ++s2) {
;         u32x4 w; w.x = pk2n(S[8 * s2 + 0], S[8 * s2 + 1]); w.y = pk2n(S[8 * s2 + 2], S[8 * s2 + 3]); w.z = pk2n(S[8 * s2 + 4], S[8 * s2 + 5]); w.w = pk2n(S[8 * s2 + 6], S[8 * s2 + 7]);
;         pf[s2] = __builtin_bit_cast(bf16x8, w);
;     }
; #pragma unroll
;     for (int s2 = 0; s2 < 2; ++s2) {
;         o0 = __builtin_amdgcn_mfma_f32_32x32x16_bf16(vf[s2][0], pf[s2], o0, 0, 0, 0);
;         o1 = __builtin_amdgcn_mfma_f32_32x32x16_bf16(vf[s2][1], pf[s2], o1, 0, 0, 0);
;     }
; __device__ __forceinline__ void attnA_unit(const Args& a, int unit, LAS unsigned char* lds) {
;     ...
;             const float lt = l + __shfl_xor(l, 32);
;             const float inv = 1.0f / lt, lse = m + __builtin_amdgcn_logf(lt);
;             const size_t tokg = (size_t)b * SEQ + tq;
;             if (pidx < 2) {
;                 bf16_t* op = OA + ((size_t)pidx * MTOK + tokg) * 384 + 64 * hh;
; #pragma unroll
;                 for (int dt = 0; dt < 2; ++dt)
; #pragma unroll
;                     for (int g = 0; g < 4; ++g) {
;                         const f32x16& o = dt ? o1 : o0;
;                         u32x2 w; w.x = pk2(o[4 * g] * inv, o[4 * g + 1] * inv); w.y = pk2(o[4 * g + 2] * inv, o[4 * g + 3] * inv);
;                         *(u32x2*)(op + 32 * dt + 8 * g + 4 * h) = w;
;                     }
;                 if (h == 0) LSE[((size_t)pidx * MTOK + tokg) * 6 + hh] = lse;
	v_exp_f32_e32 v42, v42
	v_exp_f32_e32 v106, v106
	v_exp_f32_e32 v43, v43
	v_exp_f32_e32 v107, v107
	v_pk_add_f32 v[152:153], v[152:153], v[42:43]
	v_pk_add_f32 v[218:219], v[218:219], v[106:107]
	v_exp_f32_e32 v44, v44
	v_exp_f32_e32 v108, v108
	v_exp_f32_e32 v45, v45
	v_exp_f32_e32 v109, v109
	v_pk_add_f32 v[152:153], v[152:153], v[44:45]
	v_pk_add_f32 v[218:219], v[218:219], v[108:109]
	v_exp_f32_e32 v46, v46
	v_exp_f32_e32 v110, v110
	v_exp_f32_e32 v47, v47
	v_exp_f32_e32 v111, v111
	v_pk_add_f32 v[152:153], v[152:153], v[46:47]
	v_pk_add_f32 v[218:219], v[218:219], v[110:111]
	s_nop 0
	s_nop 0
	v_add_f32_e32 v152, v152, v153
	v_add_f32_e32 v218, v218, v219
	v_fma_f32 v135, v135, v140, v152
	v_fma_f32 v213, v213, v150, v218
	v_cvt_pk_bf16_f32 v32, v32, v33
	v_cvt_pk_bf16_f32 v96, v96, v97
	v_cvt_pk_bf16_f32 v33, v34, v35
	v_cvt_pk_bf16_f32 v97, v98, v99
	v_cvt_pk_bf16_f32 v34, v36, v37
	v_cvt_pk_bf16_f32 v98, v100, v101
	v_cvt_pk_bf16_f32 v35, v38, v39
	v_cvt_pk_bf16_f32 v99, v102, v103
	v_cvt_pk_bf16_f32 v36, v40, v41
	v_cvt_pk_bf16_f32 v100, v104, v105
	v_cvt_pk_bf16_f32 v37, v42, v43
	v_cvt_pk_bf16_f32 v101, v106, v107
	v_cvt_pk_bf16_f32 v38, v44, v45
	v_cvt_pk_bf16_f32 v102, v108, v109
	v_cvt_pk_bf16_f32 v39, v46, v47
	v_cvt_pk_bf16_f32 v103, v110, v111
	s_nop 0
	v_mfma_f32_32x32x16_bf16 v[16:31], v[160:163], v[32:35], v[16:31]
	v_mfma_f32_32x32x16_bf16 v[80:95], v[176:179], v[96:99], v[80:95]
	v_mfma_f32_32x32x16_bf16 v[0:15], v[164:167], v[32:35], v[0:15]
	v_mfma_f32_32x32x16_bf16 v[64:79], v[180:183], v[96:99], v[64:79]
	v_mfma_f32_32x32x16_bf16 v[16:31], v[168:171], v[36:39], v[16:31]
	v_mfma_f32_32x32x16_bf16 v[80:95], v[184:187], v[100:103], v[80:95]
	v_mfma_f32_32x32x16_bf16 v[0:15], v[172:175], v[36:39], v[0:15]
	v_mfma_f32_32x32x16_bf16 v[64:79], v[188:191], v[100:103], v[64:79]
	s_add_i32 s86, s86, 1
	s_add_i32 s2, s2, 1
	s_cmp_le_u32 s86, s87
	s_cbranch_scc1 .LaT_loop
	s_cmp_le_u32 s2, s3
	s_cbranch_scc1 .LaT_loop
	s_nop 15
	s_nop 7
	s_lshl_b32 s32, s83, 13
	v_mov_b32_e32 v39, v135
	s_nop 1
	v_permlane32_swap_b32_e32 v39, v135
	v_add_f32_e32 v63, v135, v39
	v_add_u32_e32 v40, s32, v192
	v_log_f32_e32 v34, v63
	v_div_scale_f32 v35, s[0:1], v63, v63, 1.0
	v_rcp_f32_e32 v37, v35
	v_div_scale_f32 v38, vcc, 1.0, v63, 1.0
	v_fma_f32 v62, -v35, v37, 1.0
	v_fmac_f32_e32 v37, v62, v37
	v_mul_f32_e32 v62, v38, v37
	v_fma_f32 v33, -v35, v62, v38
	v_fmac_f32_e32 v62, v33, v37
	v_fma_f32 v35, -v35, v62, v38
	v_div_fmas_f32 v35, v35, v37, v62
	v_div_fixup_f32 v33, v35, v63, 1.0
	v_add_f32_e32 v36, v137, v34
	s_lshl_b32 s80, 8, s73
	s_and_b64 vcc, exec, s[90:91]
	s_cbranch_vccz .LaT_mga
	v_mul_f32_e32 v52, v16, v33
	v_mul_f32_e32 v53, v17, v33
	v_mul_f32_e32 v54, v18, v33
	v_mul_f32_e32 v55, v19, v33
	v_cvt_pk_bf16_f32 v48, v52, v53
	v_cvt_pk_bf16_f32 v49, v54, v55
	v_xor_b32_e32 v41, 0x0, v40
	ds_write_b64 v41, v[48:49]
	v_mul_f32_e32 v52, v20, v33
	v_mul_f32_e32 v53, v21, v33
	v_mul_f32_e32 v54, v22, v33
	v_mul_f32_e32 v55, v23, v33
	v_cvt_pk_bf16_f32 v50, v52, v53
	v_cvt_pk_bf16_f32 v51, v54, v55
	v_xor_b32_e32 v41, 0x10, v40
	ds_write_b64 v41, v[50:51]
	v_mul_f32_e32 v52, v24, v33
	v_mul_f32_e32 v53, v25, v33
	v_mul_f32_e32 v54, v26, v33
	v_mul_f32_e32 v55, v27, v33
	v_cvt_pk_bf16_f32 v48, v52, v53
	v_cvt_pk_bf16_f32 v49, v54, v55
	v_xor_b32_e32 v41, 0x20, v40
	ds_write_b64 v41, v[48:49]
	v_mul_f32_e32 v52, v28, v33
	v_mul_f32_e32 v53, v29, v33
	v_mul_f32_e32 v54, v30, v33
	v_mul_f32_e32 v55, v31, v33
	v_cvt_pk_bf16_f32 v50, v52, v53
	v_cvt_pk_bf16_f32 v51, v54, v55
	v_xor_b32_e32 v41, 0x30, v40
	ds_write_b64 v41, v[50:51]
	v_mul_f32_e32 v52, v0, v33
	v_mul_f32_e32 v53, v1, v33
	v_mul_f32_e32 v54, v2, v33
	v_mul_f32_e32 v55, v3, v33
	v_cvt_pk_bf16_f32 v48, v52, v53
	v_cvt_pk_bf16_f32 v49, v54, v55
	v_xor_b32_e32 v41, 0x40, v40
	ds_write_b64 v41, v[48:49]
	v_mul_f32_e32 v52, v4, v33
	v_mul_f32_e32 v53, v5, v33
	v_mul_f32_e32 v54, v6, v33
	v_mul_f32_e32 v55, v7, v33
	v_cvt_pk_bf16_f32 v50, v52, v53
	v_cvt_pk_bf16_f32 v51, v54, v55
	v_xor_b32_e32 v41, 0x50, v40
	ds_write_b64 v41, v[50:51]
	v_mul_f32_e32 v52, v8, v33
	v_mul_f32_e32 v53, v9, v33
	v_mul_f32_e32 v54, v10, v33
	v_mul_f32_e32 v55, v11, v33
	v_cvt_pk_bf16_f32 v48, v52, v53
	v_cvt_pk_bf16_f32 v49, v54, v55
	v_xor_b32_e32 v41, 0x60, v40
	ds_write_b64 v41, v[48:49]
	v_mul_f32_e32 v52, v12, v33
	v_mul_f32_e32 v53, v13, v33
	v_mul_f32_e32 v54, v14, v33
	v_mul_f32_e32 v55, v15, v33
	v_cvt_pk_bf16_f32 v50, v52, v53
	v_cvt_pk_bf16_f32 v51, v54, v55
	v_xor_b32_e32 v41, 0x70, v40
	ds_write_b64 v41, v[50:51]
	v_readlane_b32 s0, v253, 6
	s_movk_i32 s1, 0x300
	v_add_u32_e32 v43, s0, v142
	v_add_u32_e32 v56, s0, v122
	v_mov_b32_e32 v44, s94
	v_mov_b32_e32 v45, s95
	v_add_co_u32_e32 v44, vcc, v44, v147
	s_nop 0
	v_addc_co_u32_e32 v45, vcc, 0, v45, vcc
	s_and_saveexec_b64 s[2:3], s[70:71]
	v_mad_u64_u32 v[58:59], s[98:99], v56, 24, s[88:89]
	global_store_dword v[58:59], v36, off
	s_or_b64 exec, exec, s[2:3]
	s_branch .LaT_fla
; __device__ __forceinline__ unsigned pk2(float lo, float hi) { unsigned r; asm("v_cvt_pk_bf16_f32 %0, %1, %2" : "=v"(r) : "v"(lo), "v"(hi)); return r; }
; __device__ __forceinline__ float bflo(unsigned w) { return __uint_as_float(w << 16); }
; __device__ __forceinline__ float bfhi(unsigned w) { return __uint_as_float(w & 0xffff0000u); }
; __device__ __forceinline__ float fexp2(float x) { return __builtin_amdgcn_exp2f(x); }
; __device__ __forceinline__ void attnA_unit(const Args& a, int unit, LAS unsigned char* lds) {
;     ...
;             } else {
;                 const float l1 = LSE[tokg * 6 + hh], l2 = LSE[((size_t)MTOK + tokg) * 6 + hh];
;                 const float mx = fmaxf(lse, fmaxf(l1, l2));
;                 const float w1 = fexp2(l1 - mx), w2 = fexp2(l2 - mx), w3 = fexp2(lse - mx);
;                 const float wi = 1.0f / (w1 + w2 + w3);
;                 const float c1 = w1 * wi, c2 = w2 * wi, c3 = w3 * wi * inv;
;                 const bf16_t* p1 = OA + tokg * 384 + 64 * hh; const bf16_t* p2 = OA + ((size_t)MTOK + tokg) * 384 + 64 * hh;
;                 bf16_t* op = MIX + tokg * DM + 64 * hh;
; #pragma unroll
;                 for (int dt = 0; dt < 2; ++dt)
; #pragma unroll
;                     for (int g = 0; g < 4; ++g) {
;                         const f32x16& o = dt ? o1 : o0;
;                         const int d = 32 * dt + 8 * g + 4 * h;
;                         const u32x2 a1 = *(const u32x2*)(p1 + d), a2 = *(const u32x2*)(p2 + d);
;                         const float r0 = c1 * bflo(a1.x) + c2 * bflo(a2.x) + c3 * o[4 * g], r1 = c1 * bfhi(a1.x) + c2 * bfhi(a2.x) + c3 * o[4 * g + 1];
;                         const float r2 = c1 * bflo(a1.y) + c2 * bflo(a2.y) + c3 * o[4 * g + 2], r3 = c1 * bfhi(a1.y) + c2 * bfhi(a2.y) + c3 * o[4 * g + 3];
;                         u32x2 w; w.x = pk2(r0, r1); w.y = pk2(r2, r3);
;                         *(u32x2*)(op + d) = w;
;                     }
.LaT_mga:
	s_lshl_b32 s32, s83, 13
	s_lshl_b32 s80, 8, s73
	v_mad_u64_u32 v[58:59], s[98:99], v122, 24, s[88:89]
	global_load_dword v103, v[58:59], off
	v_add_co_u32_e32 v58, vcc, 0x180000, v58
	s_nop 0
	v_addc_co_u32_e32 v59, vcc, 0, v59, vcc
	global_load_dword v104, v[58:59], off
	v_mov_b32_e32 v58, s94
	v_mov_b32_e32 v59, s95
	v_add_co_u32_e32 v58, vcc, v58, v194
	s_movk_i32 s1, 0x300
	v_addc_co_u32_e32 v59, vcc, 0, v59, vcc
	v_mov_b32_e32 v43, v142
	v_mad_u64_u32 v[60:61], s[98:99], v43, s1, v[58:59]
	s_add_i32 m0, s32, 0x0
	s_nop 0
	global_load_lds_dwordx4 v[60:61], off
	v_add_u32_e32 v43, s80, v43
	v_mad_u64_u32 v[60:61], s[98:99], v43, s1, v[58:59]
	s_add_i32 m0, s32, 0x400
	s_nop 0
	global_load_lds_dwordx4 v[60:61], off
	v_add_u32_e32 v43, s80, v43
	v_mad_u64_u32 v[60:61], s[98:99], v43, s1, v[58:59]
	s_add_i32 m0, s32, 0x800
	s_nop 0
	global_load_lds_dwordx4 v[60:61], off
	v_add_u32_e32 v43, s80, v43
	v_mad_u64_u32 v[60:61], s[98:99], v43, s1, v[58:59]
	s_add_i32 m0, s32, 0xc00
	s_nop 0
	global_load_lds_dwordx4 v[60:61], off
	v_add_u32_e32 v43, 0x10000, v142
	v_mad_u64_u32 v[60:61], s[98:99], v43, s1, v[58:59]
	s_add_i32 m0, s32, 0x1000
	s_nop 0
	global_load_lds_dwordx4 v[60:61], off
	v_add_u32_e32 v43, s80, v43
	v_mad_u64_u32 v[60:61], s[98:99], v43, s1, v[58:59]
	s_add_i32 m0, s32, 0x1400
	s_nop 0
	global_load_lds_dwordx4 v[60:61], off
	v_add_u32_e32 v43, s80, v43
	v_mad_u64_u32 v[60:61], s[98:99], v43, s1, v[58:59]
	s_add_i32 m0, s32, 0x1800
	s_nop 0
	global_load_lds_dwordx4 v[60:61], off
	v_add_u32_e32 v43, s80, v43
	v_mad_u64_u32 v[60:61], s[98:99], v43, s1, v[58:59]
	s_add_i32 m0, s32, 0x1c00
	s_nop 0
	global_load_lds_dwordx4 v[60:61], off
	s_waitcnt vmcnt(0)
	v_xor_b32_e32 v41, 0x0, v40
	ds_read_b64 v[160:161], v41
	ds_read_b64 v[176:177], v41 offset:4096
	v_xor_b32_e32 v41, 0x10, v40
	ds_read_b64 v[162:163], v41
	ds_read_b64 v[178:179], v41 offset:4096
	v_xor_b32_e32 v41, 0x20, v40
	ds_read_b64 v[164:165], v41
	ds_read_b64 v[180:181], v41 offset:4096
	v_xor_b32_e32 v41, 0x30, v40
	ds_read_b64 v[166:167], v41
	ds_read_b64 v[182:183], v41 offset:4096
	v_xor_b32_e32 v41, 0x40, v40
	ds_read_b64 v[168:169], v41
	ds_read_b64 v[184:185], v41 offset:4096
	v_xor_b32_e32 v41, 0x50, v40
	ds_read_b64 v[170:171], v41
	ds_read_b64 v[186:187], v41 offset:4096
	v_xor_b32_e32 v41, 0x60, v40
	ds_read_b64 v[172:173], v41
	ds_read_b64 v[188:189], v41 offset:4096
	v_xor_b32_e32 v41, 0x70, v40
	ds_read_b64 v[174:175], v41
	ds_read_b64 v[190:191], v41 offset:4096
	v_max3_f32 v96, v36, v103, v104
	v_sub_f32_e32 v97, v103, v96
	v_sub_f32_e32 v98, v104, v96
	v_sub_f32_e32 v99, v36, v96
	v_exp_f32_e32 v97, v97
	v_exp_f32_e32 v98, v98
	v_exp_f32_e32 v99, v99
	s_nop 0
	v_add_f32_e32 v105, v97, v98
	v_add_f32_e32 v105, v99, v105
	v_div_scale_f32 v35, s[0:1], v105, v105, 1.0
	v_rcp_f32_e32 v37, v35
	v_div_scale_f32 v38, vcc, 1.0, v105, 1.0
	v_fma_f32 v62, -v35, v37, 1.0
	v_fmac_f32_e32 v37, v62, v37
	v_mul_f32_e32 v62, v38, v37
	v_fma_f32 v106, -v35, v62, v38
	v_fmac_f32_e32 v62, v106, v37
	v_fma_f32 v35, -v35, v62, v38
	v_div_fmas_f32 v35, v35, v37, v62
	v_div_fixup_f32 v106, v35, v105, 1.0
	v_mul_f32_e32 v100, v97, v106
	v_mul_f32_e32 v101, v98, v106
	v_mul_f32_e32 v102, v99, v106
	v_mul_f32_e32 v102, v33, v102
	s_waitcnt lgkmcnt(0)
	v_lshlrev_b32_e32 v52, 16, v160
	v_lshlrev_b32_e32 v53, 16, v176
	v_mul_f32_e32 v52, v100, v52
	v_mul_f32_e32 v54, v102, v16
	v_fmac_f32_e32 v52, v101, v53
	v_add_f32_e32 v54, v52, v54
	v_and_b32_e32 v52, 0xffff0000, v160
	v_and_b32_e32 v53, 0xffff0000, v176
	v_mul_f32_e32 v52, v100, v52
	v_mul_f32_e32 v55, v102, v17
	v_fmac_f32_e32 v52, v101, v53
	v_add_f32_e32 v55, v52, v55
	v_lshlrev_b32_e32 v52, 16, v161
	v_lshlrev_b32_e32 v53, 16, v177
	v_mul_f32_e32 v52, v100, v52
	v_mul_f32_e32 v56, v102, v18
	v_fmac_f32_e32 v52, v101, v53
	v_add_f32_e32 v56, v52, v56
	v_and_b32_e32 v52, 0xffff0000, v161
	v_and_b32_e32 v53, 0xffff0000, v177
	v_mul_f32_e32 v52, v100, v52
	v_mul_f32_e32 v57, v102, v19
	v_fmac_f32_e32 v52, v101, v53
	v_add_f32_e32 v57, v52, v57
	v_cvt_pk_bf16_f32 v48, v54, v55
	v_cvt_pk_bf16_f32 v49, v56, v57
	v_xor_b32_e32 v41, 0x0, v40
	ds_write_b64 v41, v[48:49]
	v_lshlrev_b32_e32 v52, 16, v162
	v_lshlrev_b32_e32 v53, 16, v178
	v_mul_f32_e32 v52, v100, v52
	v_mul_f32_e32 v54, v102, v20
	v_fmac_f32_e32 v52, v101, v53
	v_add_f32_e32 v54, v52, v54
	v_and_b32_e32 v52, 0xffff0000, v162
	v_and_b32_e32 v53, 0xffff0000, v178
	v_mul_f32_e32 v52, v100, v52
	v_mul_f32_e32 v55, v102, v21
	v_fmac_f32_e32 v52, v101, v53
	v_add_f32_e32 v55, v52, v55
	v_lshlrev_b32_e32 v52, 16, v163
	v_lshlrev_b32_e32 v53, 16, v179
	v_mul_f32_e32 v52, v100, v52
	v_mul_f32_e32 v56, v102, v22
	v_fmac_f32_e32 v52, v101, v53
	v_add_f32_e32 v56, v52, v56
	v_and_b32_e32 v52, 0xffff0000, v163
	v_and_b32_e32 v53, 0xffff0000, v179
	v_mul_f32_e32 v52, v100, v52
	v_mul_f32_e32 v57, v102, v23
	v_fmac_f32_e32 v52, v101, v53
	v_add_f32_e32 v57, v52, v57
	v_cvt_pk_bf16_f32 v50, v54, v55
	v_cvt_pk_bf16_f32 v51, v56, v57
	v_xor_b32_e32 v41, 0x10, v40
	ds_write_b64 v41, v[50:51]
	v_lshlrev_b32_e32 v52, 16, v164
	v_lshlrev_b32_e32 v53, 16, v180
	v_mul_f32_e32 v52, v100, v52
	v_mul_f32_e32 v54, v102, v24
	v_fmac_f32_e32 v52, v101, v53
	v_add_f32_e32 v54, v52, v54
	v_and_b32_e32 v52, 0xffff0000, v164
; __device__ __forceinline__ unsigned pk2(float lo, float hi) { unsigned r; asm("v_cvt_pk_bf16_f32 %0, %1, %2" : "=v"(r) : "v"(lo), "v"(hi)); return r; }
; __device__ __forceinline__ float bflo(unsigned w) { return __uint_as_float(w << 16); }
; __device__ __forceinline__ float bfhi(unsigned w) { return __uint_as_float(w & 0xffff0000u); }
; __device__ __forceinline__ void attnA_unit(const Args& a, int unit, LAS unsigned char* lds) {
;     ...
; #pragma unroll
;                 for (int dt = 0; dt < 2; ++dt)
; #pragma unroll
;                     for (int g = 0; g < 4; ++g) {
;                         const f32x16& o = dt ? o1 : o0;
;                         const int d = 32 * dt + 8 * g + 4 * h;
;                         const u32x2 a1 = *(const u32x2*)(p1 + d), a2 = *(const u32x2*)(p2 + d);
;                         const float r0 = c1 * bflo(a1.x) + c2 * bflo(a2.x) + c3 * o[4 * g], r1 = c1 * bfhi(a1.x) + c2 * bfhi(a2.x) + c3 * o[4 * g + 1];
;                         const float r2 = c1 * bflo(a1.y) + c2 * bflo(a2.y) + c3 * o[4 * g + 2], r3 = c1 * bfhi(a1.y) + c2 * bfhi(a2.y) + c3 * o[4 * g + 3];
;                         u32x2 w; w.x = pk2(r0, r1); w.y = pk2(r2, r3);
;                         *(u32x2*)(op + d) = w;
;                     }
	v_and_b32_e32 v53, 0xffff0000, v180
	v_mul_f32_e32 v52, v100, v52
	v_mul_f32_e32 v55, v102, v25
	v_fmac_f32_e32 v52, v101, v53
	v_add_f32_e32 v55, v52, v55
	v_lshlrev_b32_e32 v52, 16, v165
	v_lshlrev_b32_e32 v53, 16, v181
	v_mul_f32_e32 v52, v100, v52
	v_mul_f32_e32 v56, v102, v26
	v_fmac_f32_e32 v52, v101, v53
	v_add_f32_e32 v56, v52, v56
	v_and_b32_e32 v52, 0xffff0000, v165
	v_and_b32_e32 v53, 0xffff0000, v181
	v_mul_f32_e32 v52, v100, v52
	v_mul_f32_e32 v57, v102, v27
	v_fmac_f32_e32 v52, v101, v53
	v_add_f32_e32 v57, v52, v57
	v_cvt_pk_bf16_f32 v48, v54, v55
	v_cvt_pk_bf16_f32 v49, v56, v57
	v_xor_b32_e32 v41, 0x20, v40
	ds_write_b64 v41, v[48:49]
	v_lshlrev_b32_e32 v52, 16, v166
	v_lshlrev_b32_e32 v53, 16, v182
	v_mul_f32_e32 v52, v100, v52
	v_mul_f32_e32 v54, v102, v28
	v_fmac_f32_e32 v52, v101, v53
	v_add_f32_e32 v54, v52, v54
	v_and_b32_e32 v52, 0xffff0000, v166
	v_and_b32_e32 v53, 0xffff0000, v182
	v_mul_f32_e32 v52, v100, v52
	v_mul_f32_e32 v55, v102, v29
	v_fmac_f32_e32 v52, v101, v53
	v_add_f32_e32 v55, v52, v55
	v_lshlrev_b32_e32 v52, 16, v167
	v_lshlrev_b32_e32 v53, 16, v183
	v_mul_f32_e32 v52, v100, v52
	v_mul_f32_e32 v56, v102, v30
	v_fmac_f32_e32 v52, v101, v53
	v_add_f32_e32 v56, v52, v56
	v_and_b32_e32 v52, 0xffff0000, v167
	v_and_b32_e32 v53, 0xffff0000, v183
	v_mul_f32_e32 v52, v100, v52
	v_mul_f32_e32 v57, v102, v31
	v_fmac_f32_e32 v52, v101, v53
	v_add_f32_e32 v57, v52, v57
	v_cvt_pk_bf16_f32 v50, v54, v55
	v_cvt_pk_bf16_f32 v51, v56, v57
	v_xor_b32_e32 v41, 0x30, v40
	ds_write_b64 v41, v[50:51]
	v_lshlrev_b32_e32 v52, 16, v168
	v_lshlrev_b32_e32 v53, 16, v184
	v_mul_f32_e32 v52, v100, v52
	v_mul_f32_e32 v54, v102, v0
	v_fmac_f32_e32 v52, v101, v53
	v_add_f32_e32 v54, v52, v54
	v_and_b32_e32 v52, 0xffff0000, v168
	v_and_b32_e32 v53, 0xffff0000, v184
	v_mul_f32_e32 v52, v100, v52
	v_mul_f32_e32 v55, v102, v1
	v_fmac_f32_e32 v52, v101, v53
	v_add_f32_e32 v55, v52, v55
	v_lshlrev_b32_e32 v52, 16, v169
	v_lshlrev_b32_e32 v53, 16, v185
	v_mul_f32_e32 v52, v100, v52
	v_mul_f32_e32 v56, v102, v2
	v_fmac_f32_e32 v52, v101, v53
	v_add_f32_e32 v56, v52, v56
	v_and_b32_e32 v52, 0xffff0000, v169
	v_and_b32_e32 v53, 0xffff0000, v185
	v_mul_f32_e32 v52, v100, v52
	v_mul_f32_e32 v57, v102, v3
	v_fmac_f32_e32 v52, v101, v53
	v_add_f32_e32 v57, v52, v57
	v_cvt_pk_bf16_f32 v48, v54, v55
	v_cvt_pk_bf16_f32 v49, v56, v57
	v_xor_b32_e32 v41, 0x40, v40
	ds_write_b64 v41, v[48:49]
	v_lshlrev_b32_e32 v52, 16, v170
	v_lshlrev_b32_e32 v53, 16, v186
	v_mul_f32_e32 v52, v100, v52
	v_mul_f32_e32 v54, v102, v4
	v_fmac_f32_e32 v52, v101, v53
	v_add_f32_e32 v54, v52, v54
	v_and_b32_e32 v52, 0xffff0000, v170
	v_and_b32_e32 v53, 0xffff0000, v186
	v_mul_f32_e32 v52, v100, v52
	v_mul_f32_e32 v55, v102, v5
	v_fmac_f32_e32 v52, v101, v53
	v_add_f32_e32 v55, v52, v55
	v_lshlrev_b32_e32 v52, 16, v171
	v_lshlrev_b32_e32 v53, 16, v187
	v_mul_f32_e32 v52, v100, v52
	v_mul_f32_e32 v56, v102, v6
	v_fmac_f32_e32 v52, v101, v53
	v_add_f32_e32 v56, v52, v56
	v_and_b32_e32 v52, 0xffff0000, v171
	v_and_b32_e32 v53, 0xffff0000, v187
	v_mul_f32_e32 v52, v100, v52
	v_mul_f32_e32 v57, v102, v7
	v_fmac_f32_e32 v52, v101, v53
	v_add_f32_e32 v57, v52, v57
	v_cvt_pk_bf16_f32 v50, v54, v55
	v_cvt_pk_bf16_f32 v51, v56, v57
	v_xor_b32_e32 v41, 0x50, v40
	ds_write_b64 v41, v[50:51]
	v_lshlrev_b32_e32 v52, 16, v172
	v_lshlrev_b32_e32 v53, 16, v188
	v_mul_f32_e32 v52, v100, v52
	v_mul_f32_e32 v54, v102, v8
	v_fmac_f32_e32 v52, v101, v53
	v_add_f32_e32 v54, v52, v54
	v_and_b32_e32 v52, 0xffff0000, v172
	v_and_b32_e32 v53, 0xffff0000, v188
	v_mul_f32_e32 v52, v100, v52
	v_mul_f32_e32 v55, v102, v9
	v_fmac_f32_e32 v52, v101, v53
	v_add_f32_e32 v55, v52, v55
	v_lshlrev_b32_e32 v52, 16, v173
	v_lshlrev_b32_e32 v53, 16, v189
	v_mul_f32_e32 v52, v100, v52
	v_mul_f32_e32 v56, v102, v10
	v_fmac_f32_e32 v52, v101, v53
	v_add_f32_e32 v56, v52, v56
	v_and_b32_e32 v52, 0xffff0000, v173
	v_and_b32_e32 v53, 0xffff0000, v189
	v_mul_f32_e32 v52, v100, v52
	v_mul_f32_e32 v57, v102, v11
	v_fmac_f32_e32 v52, v101, v53
	v_add_f32_e32 v57, v52, v57
	v_cvt_pk_bf16_f32 v48, v54, v55
	v_cvt_pk_bf16_f32 v49, v56, v57
	v_xor_b32_e32 v41, 0x60, v40
	ds_write_b64 v41, v[48:49]
	v_lshlrev_b32_e32 v52, 16, v174
	v_lshlrev_b32_e32 v53, 16, v190
	v_mul_f32_e32 v52, v100, v52
	v_mul_f32_e32 v54, v102, v12
	v_fmac_f32_e32 v52, v101, v53
	v_add_f32_e32 v54, v52, v54
	v_and_b32_e32 v52, 0xffff0000, v174
	v_and_b32_e32 v53, 0xffff0000, v190
	v_mul_f32_e32 v52, v100, v52
	v_mul_f32_e32 v55, v102, v13
	v_fmac_f32_e32 v52, v101, v53
	v_add_f32_e32 v55, v52, v55
	v_lshlrev_b32_e32 v52, 16, v175
	v_lshlrev_b32_e32 v53, 16, v191
	v_mul_f32_e32 v52, v100, v52
	v_mul_f32_e32 v56, v102, v14
	v_fmac_f32_e32 v52, v101, v53
	v_add_f32_e32 v56, v52, v56
	v_and_b32_e32 v52, 0xffff0000, v175
	v_and_b32_e32 v53, 0xffff0000, v191
	v_mul_f32_e32 v52, v100, v52
	v_mul_f32_e32 v57, v102, v15
	v_fmac_f32_e32 v52, v101, v53
	v_add_f32_e32 v57, v52, v57
	v_cvt_pk_bf16_f32 v50, v54, v55
	v_cvt_pk_bf16_f32 v51, v56, v57
	v_xor_b32_e32 v41, 0x70, v40
	ds_write_b64 v41, v[50:51]
	s_movk_i32 s1, 0x800
	v_mov_b32_e32 v43, v142
	v_sub_u32_e32 v46, v147, v154
	v_ashrrev_i32_e32 v47, 31, v46
	v_add_co_u32_e32 v44, vcc, v118, v46
	s_nop 0
	v_addc_co_u32_e32 v45, vcc, v119, v47, vcc

; __device__ __forceinline__ unsigned pk2(float lo, float hi) { unsigned r; asm("v_cvt_pk_bf16_f32 %0, %1, %2" : "=v"(r) : "v"(lo), "v"(hi)); return r; }
; __device__ __forceinline__ float bflo(unsigned w) { return __uint_as_float(w << 16); }
; __device__ __forceinline__ float bfhi(unsigned w) { return __uint_as_float(w & 0xffff0000u); }
; __device__ __forceinline__ float fexp2(float x) { return __builtin_amdgcn_exp2f(x); }
; __device__ __forceinline__ void attnA_unit(const Args& a, int unit, LAS unsigned char* lds) {
;     ...
;             } else {
;                 const float l1 = LSE[tokg * 6 + hh], l2 = LSE[((size_t)MTOK + tokg) * 6 + hh];
;                 const float mx = fmaxf(lse, fmaxf(l1, l2));
;                 const float w1 = fexp2(l1 - mx), w2 = fexp2(l2 - mx), w3 = fexp2(lse - mx);
;                 const float wi = 1.0f / (w1 + w2 + w3);
;                 const float c1 = w1 * wi, c2 = w2 * wi, c3 = w3 * wi * inv;
;                 const bf16_t* p1 = OA + tokg * 384 + 64 * hh; const bf16_t* p2 = OA + ((size_t)MTOK + tokg) * 384 + 64 * hh;
;                 bf16_t* op = MIX + tokg * DM + 64 * hh;
; #pragma unroll
;                 for (int dt = 0; dt < 2; ++dt)
; #pragma unroll
;                     for (int g = 0; g < 4; ++g) {
;                         const f32x16& o = dt ? o1 : o0;
;                         const int d = 32 * dt + 8 * g + 4 * h;
;                         const u32x2 a1 = *(const u32x2*)(p1 + d), a2 = *(const u32x2*)(p2 + d);
;                         const float r0 = c1 * bflo(a1.x) + c2 * bflo(a2.x) + c3 * o[4 * g], r1 = c1 * bfhi(a1.x) + c2 * bfhi(a2.x) + c3 * o[4 * g + 1];
;                         const float r2 = c1 * bflo(a1.y) + c2 * bflo(a2.y) + c3 * o[4 * g + 2], r3 = c1 * bfhi(a1.y) + c2 * bfhi(a2.y) + c3 * o[4 * g + 3];
;                         u32x2 w; w.x = pk2(r0, r1); w.y = pk2(r2, r3);
;                         *(u32x2*)(op + d) = w;
;                     }
.LaT_mgb:
	s_lshl_b32 s32, s83, 13
	s_add_i32 s32, s32, 0x2000
	s_lshl_b32 s80, 8, s73
	v_mad_u64_u32 v[58:59], s[98:99], v216, 24, s[88:89]
	global_load_dword v107, v[58:59], off
	v_add_co_u32_e32 v58, vcc, 0x180000, v58
	s_nop 0
	v_addc_co_u32_e32 v59, vcc, 0, v59, vcc
	global_load_dword v108, v[58:59], off
	v_mov_b32_e32 v58, s94
	v_mov_b32_e32 v59, s95
	v_add_co_u32_e32 v58, vcc, v58, v194
	s_movk_i32 s1, 0x300
	v_addc_co_u32_e32 v59, vcc, 0, v59, vcc
	v_mov_b32_e32 v43, v224
	v_mad_u64_u32 v[60:61], s[98:99], v43, s1, v[58:59]
	s_add_i32 m0, s32, 0x0
	s_nop 0
	global_load_lds_dwordx4 v[60:61], off
	v_add_u32_e32 v43, s80, v43
	v_mad_u64_u32 v[60:61], s[98:99], v43, s1, v[58:59]
	s_add_i32 m0, s32, 0x400
	s_nop 0
	global_load_lds_dwordx4 v[60:61], off
	v_add_u32_e32 v43, s80, v43
	v_mad_u64_u32 v[60:61], s[98:99], v43, s1, v[58:59]
	s_add_i32 m0, s32, 0x800
	s_nop 0
	global_load_lds_dwordx4 v[60:61], off
	v_add_u32_e32 v43, s80, v43
	v_mad_u64_u32 v[60:61], s[98:99], v43, s1, v[58:59]
	s_add_i32 m0, s32, 0xc00
	s_nop 0
	global_load_lds_dwordx4 v[60:61], off
	v_add_u32_e32 v43, 0x10000, v224
	v_mad_u64_u32 v[60:61], s[98:99], v43, s1, v[58:59]
	s_add_i32 m0, s32, 0x1000
	s_nop 0
	global_load_lds_dwordx4 v[60:61], off
	v_add_u32_e32 v43, s80, v43
	v_mad_u64_u32 v[60:61], s[98:99], v43, s1, v[58:59]
	s_add_i32 m0, s32, 0x1400
	s_nop 0
	global_load_lds_dwordx4 v[60:61], off
	v_add_u32_e32 v43, s80, v43
	v_mad_u64_u32 v[60:61], s[98:99], v43, s1, v[58:59]
	s_add_i32 m0, s32, 0x1800
	s_nop 0
	global_load_lds_dwordx4 v[60:61], off
	v_add_u32_e32 v43, s80, v43
	v_mad_u64_u32 v[60:61], s[98:99], v43, s1, v[58:59]
	s_add_i32 m0, s32, 0x1c00
	s_nop 0
	global_load_lds_dwordx4 v[60:61], off
	s_waitcnt vmcnt(0)
	v_xor_b32_e32 v41, 0x0, v40
	ds_read_b64 v[160:161], v41
	ds_read_b64 v[176:177], v41 offset:4096
	v_xor_b32_e32 v41, 0x10, v40
	ds_read_b64 v[162:163], v41
	ds_read_b64 v[178:179], v41 offset:4096
	v_xor_b32_e32 v41, 0x20, v40
	ds_read_b64 v[164:165], v41
	ds_read_b64 v[180:181], v41 offset:4096
	v_xor_b32_e32 v41, 0x30, v40
	ds_read_b64 v[166:167], v41
	ds_read_b64 v[182:183], v41 offset:4096
	v_xor_b32_e32 v41, 0x40, v40
	ds_read_b64 v[168:169], v41
	ds_read_b64 v[184:185], v41 offset:4096
	v_xor_b32_e32 v41, 0x50, v40
	ds_read_b64 v[170:171], v41
	ds_read_b64 v[186:187], v41 offset:4096
	v_xor_b32_e32 v41, 0x60, v40
	ds_read_b64 v[172:173], v41
	ds_read_b64 v[188:189], v41 offset:4096
	v_xor_b32_e32 v41, 0x70, v40
	ds_read_b64 v[174:175], v41
	ds_read_b64 v[190:191], v41 offset:4096
	v_max3_f32 v96, v36, v107, v108
	v_sub_f32_e32 v97, v107, v96
	v_sub_f32_e32 v98, v108, v96
	v_sub_f32_e32 v99, v36, v96
	v_exp_f32_e32 v97, v97
	v_exp_f32_e32 v98, v98
	v_exp_f32_e32 v99, v99
	s_nop 0
	v_add_f32_e32 v105, v97, v98
	v_add_f32_e32 v105, v99, v105
	v_div_scale_f32 v35, s[0:1], v105, v105, 1.0
	v_rcp_f32_e32 v37, v35
	v_div_scale_f32 v38, vcc, 1.0, v105, 1.0
	v_fma_f32 v62, -v35, v37, 1.0
	v_fmac_f32_e32 v37, v62, v37
	v_mul_f32_e32 v62, v38, v37
	v_fma_f32 v106, -v35, v62, v38
	v_fmac_f32_e32 v62, v106, v37
	v_fma_f32 v35, -v35, v62, v38
	v_div_fmas_f32 v35, v35, v37, v62
	v_div_fixup_f32 v106, v35, v105, 1.0
	v_mul_f32_e32 v100, v97, v106
	v_mul_f32_e32 v101, v98, v106
	v_mul_f32_e32 v102, v99, v106
	v_mul_f32_e32 v102, v33, v102
	s_waitcnt lgkmcnt(0)
	v_lshlrev_b32_e32 v52, 16, v160
	v_lshlrev_b32_e32 v53, 16, v176
	v_mul_f32_e32 v52, v100, v52
	v_mul_f32_e32 v54, v102, v80
	v_fmac_f32_e32 v52, v101, v53
	v_add_f32_e32 v54, v52, v54
	v_and_b32_e32 v52, 0xffff0000, v160
	v_and_b32_e32 v53, 0xffff0000, v176
	v_mul_f32_e32 v52, v100, v52
	v_mul_f32_e32 v55, v102, v81
	v_fmac_f32_e32 v52, v101, v53
	v_add_f32_e32 v55, v52, v55
	v_lshlrev_b32_e32 v52, 16, v161
	v_lshlrev_b32_e32 v53, 16, v177
	v_mul_f32_e32 v52, v100, v52
	v_mul_f32_e32 v56, v102, v82
	v_fmac_f32_e32 v52, v101, v53
	v_add_f32_e32 v56, v52, v56
	v_and_b32_e32 v52, 0xffff0000, v161
	v_and_b32_e32 v53, 0xffff0000, v177
	v_mul_f32_e32 v52, v100, v52
	v_mul_f32_e32 v57, v102, v83
	v_fmac_f32_e32 v52, v101, v53
	v_add_f32_e32 v57, v52, v57
	v_cvt_pk_bf16_f32 v48, v54, v55
	v_cvt_pk_bf16_f32 v49, v56, v57
	v_xor_b32_e32 v41, 0x0, v40
	ds_write_b64 v41, v[48:49]
	v_lshlrev_b32_e32 v52, 16, v162
	v_lshlrev_b32_e32 v53, 16, v178
	v_mul_f32_e32 v52, v100, v52
	v_mul_f32_e32 v54, v102, v84
	v_fmac_f32_e32 v52, v101, v53
	v_add_f32_e32 v54, v52, v54
	v_and_b32_e32 v52, 0xffff0000, v162
	v_and_b32_e32 v53, 0xffff0000, v178
	v_mul_f32_e32 v52, v100, v52
	v_mul_f32_e32 v55, v102, v85
	v_fmac_f32_e32 v52, v101, v53
	v_add_f32_e32 v55, v52, v55
	v_lshlrev_b32_e32 v52, 16, v163
	v_lshlrev_b32_e32 v53, 16, v179
	v_mul_f32_e32 v52, v100, v52
	v_mul_f32_e32 v56, v102, v86
	v_fmac_f32_e32 v52, v101, v53
	v_add_f32_e32 v56, v52, v56
	v_and_b32_e32 v52, 0xffff0000, v163
	v_and_b32_e32 v53, 0xffff0000, v179
	v_mul_f32_e32 v52, v100, v52
	v_mul_f32_e32 v57, v102, v87
	v_fmac_f32_e32 v52, v101, v53
	v_add_f32_e32 v57, v52, v57
	v_cvt_pk_bf16_f32 v50, v54, v55
	v_cvt_pk_bf16_f32 v51, v56, v57
	v_xor_b32_e32 v41, 0x10, v40
	ds_write_b64 v41, v[50:51]
	v_lshlrev_b32_e32 v52, 16, v164
	v_lshlrev_b32_e32 v53, 16, v180
	v_mul_f32_e32 v52, v100, v52
	v_mul_f32_e32 v54, v102, v88
	v_fmac_f32_e32 v52, v101, v53
	v_add_f32_e32 v54, v52, v54
	v_and_b32_e32 v52, 0xffff0000, v164
; __device__ __forceinline__ unsigned pk2(float lo, float hi) { unsigned r; asm("v_cvt_pk_bf16_f32 %0, %1, %2" : "=v"(r) : "v"(lo), "v"(hi)); return r; }
; __device__ __forceinline__ float bflo(unsigned w) { return __uint_as_float(w << 16); }
; __device__ __forceinline__ float bfhi(unsigned w) { return __uint_as_float(w & 0xffff0000u); }
; __device__ __forceinline__ void attnA_unit(const Args& a, int unit, LAS unsigned char* lds) {
;     ...
; #pragma unroll
;                 for (int dt = 0; dt < 2; ++dt)
; #pragma unroll
;                     for (int g = 0; g < 4; ++g) {
;                         const f32x16& o = dt ? o1 : o0;
;                         const int d = 32 * dt + 8 * g + 4 * h;
;                         const u32x2 a1 = *(const u32x2*)(p1 + d), a2 = *(const u32x2*)(p2 + d);
;                         const float r0 = c1 * bflo(a1.x) + c2 * bflo(a2.x) + c3 * o[4 * g], r1 = c1 * bfhi(a1.x) + c2 * bfhi(a2.x) + c3 * o[4 * g + 1];
;                         const float r2 = c1 * bflo(a1.y) + c2 * bflo(a2.y) + c3 * o[4 * g + 2], r3 = c1 * bfhi(a1.y) + c2 * bfhi(a2.y) + c3 * o[4 * g + 3];
;                         u32x2 w; w.x = pk2(r0, r1); w.y = pk2(r2, r3);
;                         *(u32x2*)(op + d) = w;
;                     }
	v_and_b32_e32 v53, 0xffff0000, v180
	v_mul_f32_e32 v52, v100, v52
	v_mul_f32_e32 v55, v102, v89
	v_fmac_f32_e32 v52, v101, v53
	v_add_f32_e32 v55, v52, v55
	v_lshlrev_b32_e32 v52, 16, v165
	v_lshlrev_b32_e32 v53, 16, v181
	v_mul_f32_e32 v52, v100, v52
	v_mul_f32_e32 v56, v102, v90
	v_fmac_f32_e32 v52, v101, v53
	v_add_f32_e32 v56, v52, v56
	v_and_b32_e32 v52, 0xffff0000, v165
	v_and_b32_e32 v53, 0xffff0000, v181
	v_mul_f32_e32 v52, v100, v52
	v_mul_f32_e32 v57, v102, v91
	v_fmac_f32_e32 v52, v101, v53
	v_add_f32_e32 v57, v52, v57
	v_cvt_pk_bf16_f32 v48, v54, v55
	v_cvt_pk_bf16_f32 v49, v56, v57
	v_xor_b32_e32 v41, 0x20, v40
	ds_write_b64 v41, v[48:49]
	v_lshlrev_b32_e32 v52, 16, v166
	v_lshlrev_b32_e32 v53, 16, v182
	v_mul_f32_e32 v52, v100, v52
	v_mul_f32_e32 v54, v102, v92
	v_fmac_f32_e32 v52, v101, v53
	v_add_f32_e32 v54, v52, v54
	v_and_b32_e32 v52, 0xffff0000, v166
	v_and_b32_e32 v53, 0xffff0000, v182
	v_mul_f32_e32 v52, v100, v52
	v_mul_f32_e32 v55, v102, v93
	v_fmac_f32_e32 v52, v101, v53
	v_add_f32_e32 v55, v52, v55
	v_lshlrev_b32_e32 v52, 16, v167
	v_lshlrev_b32_e32 v53, 16, v183
	v_mul_f32_e32 v52, v100, v52
	v_mul_f32_e32 v56, v102, v94
	v_fmac_f32_e32 v52, v101, v53
	v_add_f32_e32 v56, v52, v56
	v_and_b32_e32 v52, 0xffff0000, v167
	v_and_b32_e32 v53, 0xffff0000, v183
	v_mul_f32_e32 v52, v100, v52
	v_mul_f32_e32 v57, v102, v95
	v_fmac_f32_e32 v52, v101, v53
	v_add_f32_e32 v57, v52, v57
	v_cvt_pk_bf16_f32 v50, v54, v55
	v_cvt_pk_bf16_f32 v51, v56, v57
	v_xor_b32_e32 v41, 0x30, v40
	ds_write_b64 v41, v[50:51]
	v_lshlrev_b32_e32 v52, 16, v168
	v_lshlrev_b32_e32 v53, 16, v184
	v_mul_f32_e32 v52, v100, v52
	v_mul_f32_e32 v54, v102, v64
	v_fmac_f32_e32 v52, v101, v53
	v_add_f32_e32 v54, v52, v54
	v_and_b32_e32 v52, 0xffff0000, v168
	v_and_b32_e32 v53, 0xffff0000, v184
	v_mul_f32_e32 v52, v100, v52
	v_mul_f32_e32 v55, v102, v65
	v_fmac_f32_e32 v52, v101, v53
	v_add_f32_e32 v55, v52, v55
	v_lshlrev_b32_e32 v52, 16, v169
	v_lshlrev_b32_e32 v53, 16, v185
	v_mul_f32_e32 v52, v100, v52
	v_mul_f32_e32 v56, v102, v66
	v_fmac_f32_e32 v52, v101, v53
	v_add_f32_e32 v56, v52, v56
	v_and_b32_e32 v52, 0xffff0000, v169
	v_and_b32_e32 v53, 0xffff0000, v185
	v_mul_f32_e32 v52, v100, v52
	v_mul_f32_e32 v57, v102, v67
	v_fmac_f32_e32 v52, v101, v53
	v_add_f32_e32 v57, v52, v57
	v_cvt_pk_bf16_f32 v48, v54, v55
	v_cvt_pk_bf16_f32 v49, v56, v57
	v_xor_b32_e32 v41, 0x40, v40
	ds_write_b64 v41, v[48:49]
	v_lshlrev_b32_e32 v52, 16, v170
	v_lshlrev_b32_e32 v53, 16, v186
	v_mul_f32_e32 v52, v100, v52
	v_mul_f32_e32 v54, v102, v68
	v_fmac_f32_e32 v52, v101, v53
	v_add_f32_e32 v54, v52, v54
	v_and_b32_e32 v52, 0xffff0000, v170
	v_and_b32_e32 v53, 0xffff0000, v186
	v_mul_f32_e32 v52, v100, v52
	v_mul_f32_e32 v55, v102, v69
	v_fmac_f32_e32 v52, v101, v53
	v_add_f32_e32 v55, v52, v55
	v_lshlrev_b32_e32 v52, 16, v171
	v_lshlrev_b32_e32 v53, 16, v187
	v_mul_f32_e32 v52, v100, v52
	v_mul_f32_e32 v56, v102, v70
	v_fmac_f32_e32 v52, v101, v53
	v_add_f32_e32 v56, v52, v56
	v_and_b32_e32 v52, 0xffff0000, v171
	v_and_b32_e32 v53, 0xffff0000, v187
	v_mul_f32_e32 v52, v100, v52
	v_mul_f32_e32 v57, v102, v71
	v_fmac_f32_e32 v52, v101, v53
	v_add_f32_e32 v57, v52, v57
	v_cvt_pk_bf16_f32 v50, v54, v55
	v_cvt_pk_bf16_f32 v51, v56, v57
	v_xor_b32_e32 v41, 0x50, v40
	ds_write_b64 v41, v[50:51]
	v_lshlrev_b32_e32 v52, 16, v172
	v_lshlrev_b32_e32 v53, 16, v188
	v_mul_f32_e32 v52, v100, v52
	v_mul_f32_e32 v54, v102, v72
	v_fmac_f32_e32 v52, v101, v53
	v_add_f32_e32 v54, v52, v54
	v_and_b32_e32 v52, 0xffff0000, v172
	v_and_b32_e32 v53, 0xffff0000, v188
	v_mul_f32_e32 v52, v100, v52
	v_mul_f32_e32 v55, v102, v73
	v_fmac_f32_e32 v52, v101, v53
	v_add_f32_e32 v55, v52, v55
	v_lshlrev_b32_e32 v52, 16, v173
	v_lshlrev_b32_e32 v53, 16, v189
	v_mul_f32_e32 v52, v100, v52
	v_mul_f32_e32 v56, v102, v74
	v_fmac_f32_e32 v52, v101, v53
	v_add_f32_e32 v56, v52, v56
	v_and_b32_e32 v52, 0xffff0000, v173
	v_and_b32_e32 v53, 0xffff0000, v189
	v_mul_f32_e32 v52, v100, v52
	v_mul_f32_e32 v57, v102, v75
	v_fmac_f32_e32 v52, v101, v53
	v_add_f32_e32 v57, v52, v57
	v_cvt_pk_bf16_f32 v48, v54, v55
	v_cvt_pk_bf16_f32 v49, v56, v57
	v_xor_b32_e32 v41, 0x60, v40
	ds_write_b64 v41, v[48:49]
	v_lshlrev_b32_e32 v52, 16, v174
	v_lshlrev_b32_e32 v53, 16, v190
	v_mul_f32_e32 v52, v100, v52
	v_mul_f32_e32 v54, v102, v76
	v_fmac_f32_e32 v52, v101, v53
	v_add_f32_e32 v54, v52, v54
	v_and_b32_e32 v52, 0xffff0000, v174
	v_and_b32_e32 v53, 0xffff0000, v190
	v_mul_f32_e32 v52, v100, v52
	v_mul_f32_e32 v55, v102, v77
	v_fmac_f32_e32 v52, v101, v53
	v_add_f32_e32 v55, v52, v55
	v_lshlrev_b32_e32 v52, 16, v175
	v_lshlrev_b32_e32 v53, 16, v191
	v_mul_f32_e32 v52, v100, v52
	v_mul_f32_e32 v56, v102, v78
	v_fmac_f32_e32 v52, v101, v53
	v_add_f32_e32 v56, v52, v56
	v_and_b32_e32 v52, 0xffff0000, v175
	v_and_b32_e32 v53, 0xffff0000, v191
	v_mul_f32_e32 v52, v100, v52
	v_mul_f32_e32 v57, v102, v79
	v_fmac_f32_e32 v52, v101, v53
	v_add_f32_e32 v57, v52, v57
	v_cvt_pk_bf16_f32 v50, v54, v55
	v_cvt_pk_bf16_f32 v51, v56, v57
	v_xor_b32_e32 v41, 0x70, v40
	ds_write_b64 v41, v[50:51]
	s_movk_i32 s1, 0x800
	v_mov_b32_e32 v43, v224
	v_sub_u32_e32 v46, v147, v154
	v_ashrrev_i32_e32 v47, 31, v46
	v_add_co_u32_e32 v44, vcc, v118, v46
	s_nop 0
	v_addc_co_u32_e32 v45, vcc, v119, v47, vcc
